# QKV epilogue: q/k norm gains loaded once per tile instead of 4 serialized loads per row (16 load+store round trips per tile removed), on top of v10
# speedup vs baseline: 1.0095x; 1.0057x over previous
.LBB0_528:
	s_ashr_i32 s65, s76, 31
	s_mov_b32 s64, s76
	s_andn2_b64 vcc, exec, s[10:11]
	v_ashrrev_i32_e32 v145, 31, v144
	s_cbranch_vccnz .LBB0_530
	v_pk_mul_f32 v[172:173], v[128:129], v[170:171] op_sel_hi:[1,0]
	v_pk_mul_f32 v[174:175], v[126:127], v[170:171] op_sel_hi:[1,0]
	v_pk_mul_f32 v[126:127], v[172:173], v[172:173]
	v_pk_mul_f32 v[128:129], v[174:175], v[174:175]
	v_pk_mul_f32 v[178:179], v[122:123], v[170:171] op_sel_hi:[1,0]
	v_pk_mov_b32 v[176:177], v[128:129], v[126:127] op_sel:[1,0]
	v_mov_b32_e32 v129, v127
	v_pk_add_f32 v[126:127], v[176:177], v[128:129]
	v_pk_mul_f32 v[176:177], v[124:125], v[170:171] op_sel_hi:[1,0]
	v_pk_mul_f32 v[124:125], v[178:179], v[178:179]
	v_pk_mul_f32 v[122:123], v[176:177], v[176:177]
	v_pk_mul_f32 v[128:129], v[118:119], v[170:171] op_sel_hi:[1,0]
	v_pk_add_f32 v[180:181], v[126:127], v[126:127] op_sel_hi:[0,1]
	v_pk_mov_b32 v[126:127], v[124:125], v[122:123] op_sel:[1,0]
	v_mov_b32_e32 v125, v123
	v_mul_f32_e32 v118, v128, v128
	v_pk_add_f32 v[122:123], v[126:127], v[124:125]
	v_pk_mul_f32 v[126:127], v[120:121], v[170:171] op_sel_hi:[1,0]
	v_pk_fma_f32 v[118:119], v[128:129], v[128:129], v[118:119] op_sel_hi:[1,1,0]
	v_pk_add_f32 v[202:203], v[122:123], v[122:123] op_sel_hi:[0,1]
	v_mul_f32_e32 v118, v126, v126
	v_pk_fma_f32 v[120:121], v[126:127], v[126:127], v[118:119] op_sel_hi:[1,1,0]
	v_pk_mul_f32 v[122:123], v[116:117], v[170:171] op_sel_hi:[1,0]
	v_pk_mul_f32 v[124:125], v[114:115], v[170:171] op_sel_hi:[1,0]
	v_mul_f32_e32 v180, v122, v122
	v_mul_f32_e32 v118, v124, v124
	v_mul_f32_e32 v120, v125, v125
	v_mul_f32_e32 v202, v123, v123
	v_pk_add_f32 v[114:115], v[118:119], v[120:121]
	v_pk_add_f32 v[116:117], v[180:181], v[202:203]
	s_and_b64 s[4:5], s[42:43], exec
	v_pk_add_f32 v[114:115], v[114:115], v[116:117]
	s_nop 0
	v_add_f32_e32 v114, v114, v115
	ds_bpermute_b32 v115, v185, v114
	s_waitcnt lgkmcnt(0)
	v_add_f32_e32 v114, v114, v115
	ds_bpermute_b32 v115, v184, v114
	s_waitcnt lgkmcnt(0)
	v_add_f32_e32 v114, v114, v115
	v_fmamk_f32 v114, v114, 0x3c800000, v243
	s_nop 1
	s_cselect_b32 s4, s27, s39
	s_cselect_b32 s5, s26, s38
	v_rsq_f32_e32 v116, v114
	s_nop 0
	v_mov_b32_e32 v114, s5
	v_mov_b32_e32 v115, s4
	v_mul_f32_e32 v117, 0x3e38aa3b, v116
	v_readlane_b32 s4, v251, 43
	v_cndmask_b32_e64 v170, v116, v117, s[42:43]
	v_lshlrev_b64 v[116:117], 11, v[168:169]
	v_readlane_b32 s5, v251, 44
	v_lshl_add_u64 v[180:181], v[144:145], 2, v[114:115]
	s_nop 0
	v_lshl_add_u64 v[118:119], s[4:5], 0, v[116:117]
	v_readlane_b32 s4, v253, 16
	v_readlane_b32 s5, v253, 17
	v_lshl_add_u64 v[118:119], s[64:65], 1, v[118:119]
	s_nop 0
	v_lshl_add_u64 v[116:117], s[4:5], 0, v[116:117]
	s_movk_i32 s4, 0xf800
	v_lshl_add_u64 v[116:117], s[76:77], 1, v[116:117]
	s_mov_b32 s5, -1
	v_lshl_add_u64 v[116:117], v[116:117], 0, s[4:5]
	v_cndmask_b32_e64 v169, v117, v119, s[42:43]
	v_cndmask_b32_e64 v168, v116, v118, s[42:43]
	global_load_dwordx4 v[216:219], v[180:181], off offset:16
	global_load_dwordx4 v[212:215], v[180:181], off
	global_load_dwordx4 v[204:207], v[180:181], off offset:144
	global_load_dwordx4 v[220:223], v[180:181], off offset:128
	s_waitcnt vmcnt(0)
	v_lshl_add_u64 v[168:169], v[144:145], 1, v[168:169]
	v_pk_mul_f32 v[116:117], v[176:177], v[218:219]
	v_pk_mul_f32 v[120:121], v[172:173], v[214:215]
	v_pk_mul_f32 v[118:119], v[174:175], v[212:213]
	v_pk_mul_f32 v[114:115], v[178:179], v[216:217]
	v_pk_mul_f32 v[120:121], v[170:171], v[120:121] op_sel_hi:[0,1]
	v_pk_mul_f32 v[118:119], v[170:171], v[118:119] op_sel_hi:[0,1]
	v_pk_mul_f32 v[172:173], v[170:171], v[116:117] op_sel_hi:[0,1]
	v_pk_mul_f32 v[116:117], v[170:171], v[114:115] op_sel_hi:[0,1]
	v_cvt_pk_bf16_f32 v114, v118, v119
	v_cvt_pk_bf16_f32 v115, v120, v121
	v_cvt_pk_bf16_f32 v116, v116, v117
	v_cvt_pk_bf16_f32 v117, v172, v173
	global_store_dwordx4 v[168:169], v[114:117], off
	s_nop 1
	v_pk_mul_f32 v[116:117], v[122:123], v[206:207]
	v_pk_mul_f32 v[120:121], v[126:127], v[222:223]
	v_pk_mul_f32 v[118:119], v[128:129], v[220:221]
	v_pk_mul_f32 v[114:115], v[124:125], v[204:205]
	v_pk_mul_f32 v[120:121], v[170:171], v[120:121] op_sel_hi:[0,1]
	v_pk_mul_f32 v[118:119], v[170:171], v[118:119] op_sel_hi:[0,1]
	v_pk_mul_f32 v[122:123], v[170:171], v[116:117] op_sel_hi:[0,1]
	v_pk_mul_f32 v[116:117], v[170:171], v[114:115] op_sel_hi:[0,1]
	v_cvt_pk_bf16_f32 v114, v118, v119
	v_cvt_pk_bf16_f32 v115, v120, v121
	v_cvt_pk_bf16_f32 v116, v116, v117
	v_cvt_pk_bf16_f32 v117, v122, v123
	global_store_dwordx4 v[168:169], v[114:117], off offset:64
	s_nop 1

.LBB0_532:
	v_readlane_b32 s4, v253, 16
	s_andn2_b64 vcc, exec, s[0:1]
	v_readlane_b32 s5, v253, 17
	s_cbranch_vccnz .LBB0_534
	v_pk_mul_f32 v[114:115], v[112:113], v[122:123] op_sel_hi:[1,0]
	v_pk_mul_f32 v[116:117], v[110:111], v[122:123] op_sel_hi:[1,0]
	v_pk_mul_f32 v[110:111], v[114:115], v[114:115]
	v_pk_mul_f32 v[112:113], v[116:117], v[116:117]
	v_pk_mul_f32 v[120:121], v[106:107], v[122:123] op_sel_hi:[1,0]
	v_pk_mov_b32 v[118:119], v[112:113], v[110:111] op_sel:[1,0]
	v_mov_b32_e32 v113, v111
	v_pk_add_f32 v[110:111], v[118:119], v[112:113]
	v_pk_mul_f32 v[118:119], v[108:109], v[122:123] op_sel_hi:[1,0]
	v_pk_mul_f32 v[108:109], v[120:121], v[120:121]
	v_pk_mul_f32 v[106:107], v[118:119], v[118:119]
	v_pk_mul_f32 v[112:113], v[102:103], v[122:123] op_sel_hi:[1,0]
	v_pk_add_f32 v[124:125], v[110:111], v[110:111] op_sel_hi:[0,1]
	v_pk_mov_b32 v[110:111], v[108:109], v[106:107] op_sel:[1,0]
	v_mov_b32_e32 v109, v107
	v_mul_f32_e32 v102, v112, v112
	v_pk_add_f32 v[106:107], v[110:111], v[108:109]
	v_pk_mul_f32 v[110:111], v[104:105], v[122:123] op_sel_hi:[1,0]
	v_pk_fma_f32 v[102:103], v[112:113], v[112:113], v[102:103] op_sel_hi:[1,1,0]
	v_pk_add_f32 v[126:127], v[106:107], v[106:107] op_sel_hi:[0,1]
	v_mul_f32_e32 v102, v110, v110
	v_pk_fma_f32 v[104:105], v[110:111], v[110:111], v[102:103] op_sel_hi:[1,1,0]
	v_pk_mul_f32 v[106:107], v[100:101], v[122:123] op_sel_hi:[1,0]
	v_pk_mul_f32 v[108:109], v[98:99], v[122:123] op_sel_hi:[1,0]
	v_mul_f32_e32 v124, v106, v106
	v_mul_f32_e32 v102, v108, v108
	v_mul_f32_e32 v104, v109, v109
	v_mul_f32_e32 v126, v107, v107
	v_pk_add_f32 v[98:99], v[102:103], v[104:105]
	v_pk_add_f32 v[100:101], v[124:125], v[126:127]
	s_and_b64 s[0:1], s[42:43], exec
	v_pk_add_f32 v[98:99], v[98:99], v[100:101]
	s_nop 0
	v_add_f32_e32 v98, v98, v99
	ds_bpermute_b32 v99, v185, v98
	s_waitcnt lgkmcnt(0)
	v_add_f32_e32 v98, v98, v99
	ds_bpermute_b32 v99, v184, v98
	s_waitcnt lgkmcnt(0)
	v_add_f32_e32 v98, v98, v99
	v_fmamk_f32 v98, v98, 0x3c800000, v243
	s_nop 1
	s_cselect_b32 s0, s27, s39
	s_cselect_b32 s1, s26, s38
	v_rsq_f32_e32 v100, v98
	s_nop 0
	v_mov_b32_e32 v98, s1
	v_mov_b32_e32 v99, s0
	v_mul_f32_e32 v101, 0x3e38aa3b, v100
	v_readlane_b32 s0, v251, 43
	v_cndmask_b32_e64 v122, v100, v101, s[42:43]
	v_lshlrev_b64 v[100:101], 11, v[166:167]
	v_readlane_b32 s1, v251, 44
	v_lshl_add_u64 v[126:127], v[144:145], 2, v[98:99]
	s_nop 0
	v_lshl_add_u64 v[102:103], s[0:1], 0, v[100:101]
	v_lshl_add_u64 v[100:101], s[4:5], 0, v[100:101]
	s_movk_i32 s0, 0xf800
	v_lshl_add_u64 v[100:101], s[76:77], 1, v[100:101]
	s_mov_b32 s1, -1
	v_lshl_add_u64 v[102:103], s[64:65], 1, v[102:103]
	v_lshl_add_u64 v[100:101], v[100:101], 0, s[0:1]
	v_cndmask_b32_e64 v125, v101, v103, s[42:43]
	v_cndmask_b32_e64 v124, v100, v102, s[42:43]
	v_pk_mul_f32 v[100:101], v[118:119], v[218:219]
	v_pk_mul_f32 v[104:105], v[114:115], v[214:215]
	v_pk_mul_f32 v[102:103], v[116:117], v[212:213]
	v_pk_mul_f32 v[98:99], v[120:121], v[216:217]
	v_pk_mul_f32 v[104:105], v[122:123], v[104:105] op_sel_hi:[0,1]
	v_pk_mul_f32 v[102:103], v[122:123], v[102:103] op_sel_hi:[0,1]
	v_pk_mul_f32 v[114:115], v[122:123], v[100:101] op_sel_hi:[0,1]
	v_pk_mul_f32 v[100:101], v[122:123], v[98:99] op_sel_hi:[0,1]
	v_cvt_pk_bf16_f32 v98, v102, v103
	v_cvt_pk_bf16_f32 v99, v104, v105
	v_cvt_pk_bf16_f32 v100, v100, v101
	v_cvt_pk_bf16_f32 v101, v114, v115
	v_lshl_add_u64 v[114:115], v[144:145], 1, v[124:125]
	global_store_dwordx4 v[114:115], v[98:101], off
	s_nop 1
	v_pk_mul_f32 v[100:101], v[106:107], v[206:207]
	v_pk_mul_f32 v[104:105], v[110:111], v[222:223]
	v_pk_mul_f32 v[102:103], v[112:113], v[220:221]
	v_pk_mul_f32 v[98:99], v[108:109], v[204:205]
	v_pk_mul_f32 v[104:105], v[122:123], v[104:105] op_sel_hi:[0,1]
	v_pk_mul_f32 v[102:103], v[122:123], v[102:103] op_sel_hi:[0,1]
	v_pk_mul_f32 v[106:107], v[122:123], v[100:101] op_sel_hi:[0,1]
	v_pk_mul_f32 v[100:101], v[122:123], v[98:99] op_sel_hi:[0,1]
	v_cvt_pk_bf16_f32 v98, v102, v103
	v_cvt_pk_bf16_f32 v99, v104, v105
	v_cvt_pk_bf16_f32 v100, v100, v101
	v_cvt_pk_bf16_f32 v101, v106, v107
	global_store_dwordx4 v[114:115], v[98:101], off offset:64
	s_nop 1

.LBB0_536:
	s_andn2_b64 vcc, exec, s[0:1]
	s_cbranch_vccnz .LBB0_538
	v_pk_mul_f32 v[98:99], v[96:97], v[106:107] op_sel_hi:[1,0]
	v_pk_mul_f32 v[100:101], v[94:95], v[106:107] op_sel_hi:[1,0]
	v_pk_mul_f32 v[94:95], v[98:99], v[98:99]
	v_pk_mul_f32 v[96:97], v[100:101], v[100:101]
	v_pk_mul_f32 v[104:105], v[90:91], v[106:107] op_sel_hi:[1,0]
	v_pk_mov_b32 v[102:103], v[96:97], v[94:95] op_sel:[1,0]
	v_mov_b32_e32 v97, v95
	v_pk_add_f32 v[94:95], v[102:103], v[96:97]
	v_pk_mul_f32 v[102:103], v[92:93], v[106:107] op_sel_hi:[1,0]
	v_pk_mul_f32 v[92:93], v[104:105], v[104:105]
	v_pk_mul_f32 v[90:91], v[102:103], v[102:103]
	v_pk_mul_f32 v[96:97], v[86:87], v[106:107] op_sel_hi:[1,0]
	v_pk_add_f32 v[108:109], v[94:95], v[94:95] op_sel_hi:[0,1]
	v_pk_mov_b32 v[94:95], v[92:93], v[90:91] op_sel:[1,0]
	v_mov_b32_e32 v93, v91
	v_mul_f32_e32 v86, v96, v96
	v_pk_add_f32 v[90:91], v[94:95], v[92:93]
	v_pk_mul_f32 v[94:95], v[88:89], v[106:107] op_sel_hi:[1,0]
	v_pk_fma_f32 v[86:87], v[96:97], v[96:97], v[86:87] op_sel_hi:[1,1,0]
	v_pk_add_f32 v[110:111], v[90:91], v[90:91] op_sel_hi:[0,1]
	v_mul_f32_e32 v86, v94, v94
	v_pk_fma_f32 v[88:89], v[94:95], v[94:95], v[86:87] op_sel_hi:[1,1,0]
	v_pk_mul_f32 v[90:91], v[84:85], v[106:107] op_sel_hi:[1,0]
	v_pk_mul_f32 v[92:93], v[82:83], v[106:107] op_sel_hi:[1,0]
	v_mul_f32_e32 v108, v90, v90
	v_mul_f32_e32 v86, v92, v92
	v_mul_f32_e32 v88, v93, v93
	v_mul_f32_e32 v110, v91, v91
	v_pk_add_f32 v[82:83], v[86:87], v[88:89]
	v_pk_add_f32 v[84:85], v[108:109], v[110:111]
	s_and_b64 s[0:1], s[42:43], exec
	v_pk_add_f32 v[82:83], v[82:83], v[84:85]
	s_nop 0
	v_add_f32_e32 v82, v82, v83
	ds_bpermute_b32 v83, v185, v82
	s_waitcnt lgkmcnt(0)
	v_add_f32_e32 v82, v82, v83
	ds_bpermute_b32 v83, v184, v82
	s_waitcnt lgkmcnt(0)
	v_add_f32_e32 v82, v82, v83
	v_fmamk_f32 v82, v82, 0x3c800000, v243
	s_nop 1
	s_cselect_b32 s0, s27, s39
	s_cselect_b32 s1, s26, s38
	v_rsq_f32_e32 v84, v82
	s_nop 0
	v_mov_b32_e32 v82, s1
	v_mov_b32_e32 v83, s0
	v_mul_f32_e32 v85, 0x3e38aa3b, v84
	v_readlane_b32 s0, v251, 43
	v_cndmask_b32_e64 v106, v84, v85, s[42:43]
	v_lshlrev_b64 v[84:85], 11, v[164:165]
	v_readlane_b32 s1, v251, 44
	v_lshl_add_u64 v[110:111], v[144:145], 2, v[82:83]
	s_nop 0
	v_lshl_add_u64 v[86:87], s[0:1], 0, v[84:85]
	v_lshl_add_u64 v[84:85], s[4:5], 0, v[84:85]
	s_movk_i32 s0, 0xf800
	v_lshl_add_u64 v[84:85], s[76:77], 1, v[84:85]
	s_mov_b32 s1, -1
	v_lshl_add_u64 v[86:87], s[64:65], 1, v[86:87]
	v_lshl_add_u64 v[84:85], v[84:85], 0, s[0:1]
	v_cndmask_b32_e64 v109, v85, v87, s[42:43]
	v_cndmask_b32_e64 v108, v84, v86, s[42:43]
	v_pk_mul_f32 v[84:85], v[102:103], v[218:219]
	v_pk_mul_f32 v[88:89], v[98:99], v[214:215]
	v_pk_mul_f32 v[86:87], v[100:101], v[212:213]
	v_pk_mul_f32 v[82:83], v[104:105], v[216:217]
	v_pk_mul_f32 v[88:89], v[106:107], v[88:89] op_sel_hi:[0,1]
	v_pk_mul_f32 v[86:87], v[106:107], v[86:87] op_sel_hi:[0,1]
	v_pk_mul_f32 v[98:99], v[106:107], v[84:85] op_sel_hi:[0,1]
	v_pk_mul_f32 v[84:85], v[106:107], v[82:83] op_sel_hi:[0,1]
	v_cvt_pk_bf16_f32 v82, v86, v87
	v_cvt_pk_bf16_f32 v83, v88, v89
	v_cvt_pk_bf16_f32 v84, v84, v85
	v_cvt_pk_bf16_f32 v85, v98, v99
	v_lshl_add_u64 v[98:99], v[144:145], 1, v[108:109]
	global_store_dwordx4 v[98:99], v[82:85], off
	s_nop 1
	v_pk_mul_f32 v[84:85], v[90:91], v[206:207]
	v_pk_mul_f32 v[88:89], v[94:95], v[222:223]
	v_pk_mul_f32 v[86:87], v[96:97], v[220:221]
	v_pk_mul_f32 v[82:83], v[92:93], v[204:205]
	v_pk_mul_f32 v[88:89], v[106:107], v[88:89] op_sel_hi:[0,1]
	v_pk_mul_f32 v[86:87], v[106:107], v[86:87] op_sel_hi:[0,1]
	v_pk_mul_f32 v[90:91], v[106:107], v[84:85] op_sel_hi:[0,1]
	v_pk_mul_f32 v[84:85], v[106:107], v[82:83] op_sel_hi:[0,1]
	v_cvt_pk_bf16_f32 v82, v86, v87
	v_cvt_pk_bf16_f32 v83, v88, v89
	v_cvt_pk_bf16_f32 v84, v84, v85
	v_cvt_pk_bf16_f32 v85, v90, v91
	global_store_dwordx4 v[98:99], v[82:85], off offset:64
	s_nop 1

.LBB0_540:
	s_andn2_b64 vcc, exec, s[0:1]
	s_cbranch_vccnz .LBB0_542
	v_pk_mul_f32 v[82:83], v[80:81], v[90:91] op_sel_hi:[1,0]
	v_pk_mul_f32 v[84:85], v[78:79], v[90:91] op_sel_hi:[1,0]
	v_pk_mul_f32 v[78:79], v[82:83], v[82:83]
	v_pk_mul_f32 v[80:81], v[84:85], v[84:85]
	v_pk_mul_f32 v[88:89], v[74:75], v[90:91] op_sel_hi:[1,0]
	v_pk_mov_b32 v[86:87], v[80:81], v[78:79] op_sel:[1,0]
	v_mov_b32_e32 v81, v79
	v_pk_add_f32 v[78:79], v[86:87], v[80:81]
	v_pk_mul_f32 v[86:87], v[76:77], v[90:91] op_sel_hi:[1,0]
	v_pk_mul_f32 v[76:77], v[88:89], v[88:89]
	v_pk_mul_f32 v[74:75], v[86:87], v[86:87]
	v_pk_mul_f32 v[80:81], v[70:71], v[90:91] op_sel_hi:[1,0]
	v_pk_add_f32 v[92:93], v[78:79], v[78:79] op_sel_hi:[0,1]
	v_pk_mov_b32 v[78:79], v[76:77], v[74:75] op_sel:[1,0]
	v_mov_b32_e32 v77, v75
	v_mul_f32_e32 v70, v80, v80
	v_pk_add_f32 v[74:75], v[78:79], v[76:77]
	v_pk_mul_f32 v[78:79], v[72:73], v[90:91] op_sel_hi:[1,0]
	v_pk_fma_f32 v[70:71], v[80:81], v[80:81], v[70:71] op_sel_hi:[1,1,0]
	v_pk_add_f32 v[94:95], v[74:75], v[74:75] op_sel_hi:[0,1]
	v_mul_f32_e32 v70, v78, v78
	v_pk_fma_f32 v[72:73], v[78:79], v[78:79], v[70:71] op_sel_hi:[1,1,0]
	v_pk_mul_f32 v[74:75], v[68:69], v[90:91] op_sel_hi:[1,0]
	v_pk_mul_f32 v[76:77], v[66:67], v[90:91] op_sel_hi:[1,0]
	v_mul_f32_e32 v92, v74, v74
	v_mul_f32_e32 v70, v76, v76
	v_mul_f32_e32 v72, v77, v77
	v_mul_f32_e32 v94, v75, v75
	v_pk_add_f32 v[66:67], v[70:71], v[72:73]
	v_pk_add_f32 v[68:69], v[92:93], v[94:95]
	s_and_b64 s[0:1], s[42:43], exec
	v_pk_add_f32 v[66:67], v[66:67], v[68:69]
	s_nop 0
	v_add_f32_e32 v66, v66, v67
	ds_bpermute_b32 v67, v185, v66
	s_waitcnt lgkmcnt(0)
	v_add_f32_e32 v66, v66, v67
	ds_bpermute_b32 v67, v184, v66
	s_waitcnt lgkmcnt(0)
	v_add_f32_e32 v66, v66, v67
	v_fmamk_f32 v66, v66, 0x3c800000, v243
	s_nop 1
	s_cselect_b32 s0, s27, s39
	s_cselect_b32 s1, s26, s38
	v_rsq_f32_e32 v68, v66
	s_nop 0
	v_mov_b32_e32 v66, s1
	v_mov_b32_e32 v67, s0
	v_mul_f32_e32 v69, 0x3e38aa3b, v68
	v_readlane_b32 s0, v251, 43
	v_cndmask_b32_e64 v90, v68, v69, s[42:43]
	v_lshlrev_b64 v[68:69], 11, v[162:163]
	v_readlane_b32 s1, v251, 44
	v_lshl_add_u64 v[94:95], v[144:145], 2, v[66:67]
	s_nop 0
	v_lshl_add_u64 v[70:71], s[0:1], 0, v[68:69]
	v_lshl_add_u64 v[68:69], s[4:5], 0, v[68:69]
	s_movk_i32 s0, 0xf800
	v_lshl_add_u64 v[68:69], s[76:77], 1, v[68:69]
	s_mov_b32 s1, -1
	v_lshl_add_u64 v[70:71], s[64:65], 1, v[70:71]
	v_lshl_add_u64 v[68:69], v[68:69], 0, s[0:1]
	v_cndmask_b32_e64 v93, v69, v71, s[42:43]
	v_cndmask_b32_e64 v92, v68, v70, s[42:43]
	v_pk_mul_f32 v[68:69], v[86:87], v[218:219]
	v_pk_mul_f32 v[72:73], v[82:83], v[214:215]
	v_pk_mul_f32 v[70:71], v[84:85], v[212:213]
	v_pk_mul_f32 v[66:67], v[88:89], v[216:217]
	v_pk_mul_f32 v[72:73], v[90:91], v[72:73] op_sel_hi:[0,1]
	v_pk_mul_f32 v[70:71], v[90:91], v[70:71] op_sel_hi:[0,1]
	v_pk_mul_f32 v[82:83], v[90:91], v[68:69] op_sel_hi:[0,1]
	v_pk_mul_f32 v[68:69], v[90:91], v[66:67] op_sel_hi:[0,1]
	v_cvt_pk_bf16_f32 v66, v70, v71
	v_cvt_pk_bf16_f32 v67, v72, v73
	v_cvt_pk_bf16_f32 v68, v68, v69
	v_cvt_pk_bf16_f32 v69, v82, v83
	v_lshl_add_u64 v[82:83], v[144:145], 1, v[92:93]
	global_store_dwordx4 v[82:83], v[66:69], off
	s_nop 1
	v_pk_mul_f32 v[68:69], v[74:75], v[206:207]
	v_pk_mul_f32 v[72:73], v[78:79], v[222:223]
	v_pk_mul_f32 v[70:71], v[80:81], v[220:221]
	v_pk_mul_f32 v[66:67], v[76:77], v[204:205]
	v_pk_mul_f32 v[72:73], v[90:91], v[72:73] op_sel_hi:[0,1]
	v_pk_mul_f32 v[70:71], v[90:91], v[70:71] op_sel_hi:[0,1]
	v_pk_mul_f32 v[74:75], v[90:91], v[68:69] op_sel_hi:[0,1]
	v_pk_mul_f32 v[68:69], v[90:91], v[66:67] op_sel_hi:[0,1]
	v_cvt_pk_bf16_f32 v66, v70, v71
	v_cvt_pk_bf16_f32 v67, v72, v73
	v_cvt_pk_bf16_f32 v68, v68, v69
	v_cvt_pk_bf16_f32 v69, v74, v75
	global_store_dwordx4 v[82:83], v[66:69], off offset:64
	s_nop 1

.LBB0_544:
	s_andn2_b64 vcc, exec, s[0:1]
	s_cbranch_vccnz .LBB0_546
	v_pk_mul_f32 v[66:67], v[64:65], v[74:75] op_sel_hi:[1,0]
	v_pk_mul_f32 v[68:69], v[62:63], v[74:75] op_sel_hi:[1,0]
	v_pk_mul_f32 v[62:63], v[66:67], v[66:67]
	v_pk_mul_f32 v[64:65], v[68:69], v[68:69]
	v_pk_mul_f32 v[72:73], v[58:59], v[74:75] op_sel_hi:[1,0]
	v_pk_mov_b32 v[70:71], v[64:65], v[62:63] op_sel:[1,0]
	v_mov_b32_e32 v65, v63
	v_pk_add_f32 v[62:63], v[70:71], v[64:65]
	v_pk_mul_f32 v[70:71], v[60:61], v[74:75] op_sel_hi:[1,0]
	v_pk_mul_f32 v[60:61], v[72:73], v[72:73]
	v_pk_mul_f32 v[58:59], v[70:71], v[70:71]
	v_pk_mul_f32 v[64:65], v[54:55], v[74:75] op_sel_hi:[1,0]
	v_pk_add_f32 v[76:77], v[62:63], v[62:63] op_sel_hi:[0,1]
	v_pk_mov_b32 v[62:63], v[60:61], v[58:59] op_sel:[1,0]
	v_mov_b32_e32 v61, v59
	v_mul_f32_e32 v54, v64, v64
	v_pk_add_f32 v[58:59], v[62:63], v[60:61]
	v_pk_mul_f32 v[62:63], v[56:57], v[74:75] op_sel_hi:[1,0]
	v_pk_fma_f32 v[54:55], v[64:65], v[64:65], v[54:55] op_sel_hi:[1,1,0]
	v_pk_add_f32 v[78:79], v[58:59], v[58:59] op_sel_hi:[0,1]
	v_mul_f32_e32 v54, v62, v62
	v_pk_fma_f32 v[56:57], v[62:63], v[62:63], v[54:55] op_sel_hi:[1,1,0]
	v_pk_mul_f32 v[58:59], v[52:53], v[74:75] op_sel_hi:[1,0]
	v_pk_mul_f32 v[60:61], v[50:51], v[74:75] op_sel_hi:[1,0]
	v_mul_f32_e32 v76, v58, v58
	v_mul_f32_e32 v54, v60, v60
	v_mul_f32_e32 v56, v61, v61
	v_mul_f32_e32 v78, v59, v59
	v_pk_add_f32 v[50:51], v[54:55], v[56:57]
	v_pk_add_f32 v[52:53], v[76:77], v[78:79]
	s_and_b64 s[0:1], s[42:43], exec
	v_pk_add_f32 v[50:51], v[50:51], v[52:53]
	s_nop 0
	v_add_f32_e32 v50, v50, v51
	ds_bpermute_b32 v51, v185, v50
	s_waitcnt lgkmcnt(0)
	v_add_f32_e32 v50, v50, v51
	ds_bpermute_b32 v51, v184, v50
	s_waitcnt lgkmcnt(0)
	v_add_f32_e32 v50, v50, v51
	v_fmamk_f32 v50, v50, 0x3c800000, v243
	s_nop 1
	s_cselect_b32 s0, s27, s39
	s_cselect_b32 s1, s26, s38
	v_rsq_f32_e32 v52, v50
	s_nop 0
	v_mov_b32_e32 v50, s1
	v_mov_b32_e32 v51, s0
	v_mul_f32_e32 v53, 0x3e38aa3b, v52
	v_readlane_b32 s0, v251, 43
	v_cndmask_b32_e64 v74, v52, v53, s[42:43]
	v_lshlrev_b64 v[52:53], 11, v[160:161]
	v_readlane_b32 s1, v251, 44
	v_lshl_add_u64 v[78:79], v[144:145], 2, v[50:51]
	s_nop 0
	v_lshl_add_u64 v[54:55], s[0:1], 0, v[52:53]
	v_lshl_add_u64 v[52:53], s[4:5], 0, v[52:53]
	s_movk_i32 s0, 0xf800
	v_lshl_add_u64 v[52:53], s[76:77], 1, v[52:53]
	s_mov_b32 s1, -1
	v_lshl_add_u64 v[54:55], s[64:65], 1, v[54:55]
	v_lshl_add_u64 v[52:53], v[52:53], 0, s[0:1]
	v_cndmask_b32_e64 v77, v53, v55, s[42:43]
	v_cndmask_b32_e64 v76, v52, v54, s[42:43]
	v_pk_mul_f32 v[52:53], v[70:71], v[218:219]
	v_pk_mul_f32 v[56:57], v[66:67], v[214:215]
	v_pk_mul_f32 v[54:55], v[68:69], v[212:213]
	v_pk_mul_f32 v[50:51], v[72:73], v[216:217]
	v_pk_mul_f32 v[56:57], v[74:75], v[56:57] op_sel_hi:[0,1]
	v_pk_mul_f32 v[54:55], v[74:75], v[54:55] op_sel_hi:[0,1]
	v_pk_mul_f32 v[66:67], v[74:75], v[52:53] op_sel_hi:[0,1]
	v_pk_mul_f32 v[52:53], v[74:75], v[50:51] op_sel_hi:[0,1]
	v_cvt_pk_bf16_f32 v50, v54, v55
	v_cvt_pk_bf16_f32 v51, v56, v57
	v_cvt_pk_bf16_f32 v52, v52, v53
	v_cvt_pk_bf16_f32 v53, v66, v67
	v_lshl_add_u64 v[66:67], v[144:145], 1, v[76:77]
	global_store_dwordx4 v[66:67], v[50:53], off
	s_nop 1
	v_pk_mul_f32 v[52:53], v[58:59], v[206:207]
	v_pk_mul_f32 v[56:57], v[62:63], v[222:223]
	v_pk_mul_f32 v[54:55], v[64:65], v[220:221]
	v_pk_mul_f32 v[50:51], v[60:61], v[204:205]
	v_pk_mul_f32 v[56:57], v[74:75], v[56:57] op_sel_hi:[0,1]
	v_pk_mul_f32 v[54:55], v[74:75], v[54:55] op_sel_hi:[0,1]
	v_pk_mul_f32 v[58:59], v[74:75], v[52:53] op_sel_hi:[0,1]
	v_pk_mul_f32 v[52:53], v[74:75], v[50:51] op_sel_hi:[0,1]
	v_cvt_pk_bf16_f32 v50, v54, v55
	v_cvt_pk_bf16_f32 v51, v56, v57
	v_cvt_pk_bf16_f32 v52, v52, v53
	v_cvt_pk_bf16_f32 v53, v58, v59
	global_store_dwordx4 v[66:67], v[50:53], off offset:64
	s_nop 1

.LBB0_548:
	s_andn2_b64 vcc, exec, s[0:1]
	s_cbranch_vccnz .LBB0_550
	v_pk_mul_f32 v[50:51], v[48:49], v[58:59] op_sel_hi:[1,0]
	v_pk_mul_f32 v[52:53], v[46:47], v[58:59] op_sel_hi:[1,0]
	v_pk_mul_f32 v[46:47], v[50:51], v[50:51]
	v_pk_mul_f32 v[48:49], v[52:53], v[52:53]
	v_pk_mul_f32 v[56:57], v[42:43], v[58:59] op_sel_hi:[1,0]
	v_pk_mov_b32 v[54:55], v[48:49], v[46:47] op_sel:[1,0]
	v_mov_b32_e32 v49, v47
	v_pk_add_f32 v[46:47], v[54:55], v[48:49]
	v_pk_mul_f32 v[54:55], v[44:45], v[58:59] op_sel_hi:[1,0]
	v_pk_mul_f32 v[44:45], v[56:57], v[56:57]
	v_pk_mul_f32 v[42:43], v[54:55], v[54:55]
	v_pk_mul_f32 v[48:49], v[38:39], v[58:59] op_sel_hi:[1,0]
	v_pk_add_f32 v[60:61], v[46:47], v[46:47] op_sel_hi:[0,1]
	v_pk_mov_b32 v[46:47], v[44:45], v[42:43] op_sel:[1,0]
	v_mov_b32_e32 v45, v43
	v_mul_f32_e32 v38, v48, v48
	v_pk_add_f32 v[42:43], v[46:47], v[44:45]
	v_pk_mul_f32 v[46:47], v[40:41], v[58:59] op_sel_hi:[1,0]
	v_pk_fma_f32 v[38:39], v[48:49], v[48:49], v[38:39] op_sel_hi:[1,1,0]
	v_pk_add_f32 v[62:63], v[42:43], v[42:43] op_sel_hi:[0,1]
	v_mul_f32_e32 v38, v46, v46
	v_pk_fma_f32 v[40:41], v[46:47], v[46:47], v[38:39] op_sel_hi:[1,1,0]
	v_pk_mul_f32 v[42:43], v[36:37], v[58:59] op_sel_hi:[1,0]
	v_pk_mul_f32 v[44:45], v[34:35], v[58:59] op_sel_hi:[1,0]
	v_mul_f32_e32 v60, v42, v42
	v_mul_f32_e32 v38, v44, v44
	v_mul_f32_e32 v40, v45, v45
	v_mul_f32_e32 v62, v43, v43
	v_pk_add_f32 v[34:35], v[38:39], v[40:41]
	v_pk_add_f32 v[36:37], v[60:61], v[62:63]
	s_and_b64 s[0:1], s[42:43], exec
	v_pk_add_f32 v[34:35], v[34:35], v[36:37]
	s_nop 0
	v_add_f32_e32 v34, v34, v35
	ds_bpermute_b32 v35, v185, v34
	s_waitcnt lgkmcnt(0)
	v_add_f32_e32 v34, v34, v35
	ds_bpermute_b32 v35, v184, v34
	s_waitcnt lgkmcnt(0)
	v_add_f32_e32 v34, v34, v35
	v_fmamk_f32 v34, v34, 0x3c800000, v243
	s_nop 1
	s_cselect_b32 s0, s27, s39
	s_cselect_b32 s1, s26, s38
	v_rsq_f32_e32 v36, v34
	s_nop 0
	v_mov_b32_e32 v34, s1
	v_mov_b32_e32 v35, s0
	v_mul_f32_e32 v37, 0x3e38aa3b, v36
	v_readlane_b32 s0, v251, 43
	v_cndmask_b32_e64 v58, v36, v37, s[42:43]
	v_lshlrev_b64 v[36:37], 11, v[158:159]
	v_readlane_b32 s1, v251, 44
	v_lshl_add_u64 v[62:63], v[144:145], 2, v[34:35]
	s_nop 0
	v_lshl_add_u64 v[38:39], s[0:1], 0, v[36:37]
	v_lshl_add_u64 v[36:37], s[4:5], 0, v[36:37]
	s_movk_i32 s0, 0xf800
	v_lshl_add_u64 v[36:37], s[76:77], 1, v[36:37]
	s_mov_b32 s1, -1
	v_lshl_add_u64 v[38:39], s[64:65], 1, v[38:39]
	v_lshl_add_u64 v[36:37], v[36:37], 0, s[0:1]
	v_cndmask_b32_e64 v61, v37, v39, s[42:43]
	v_cndmask_b32_e64 v60, v36, v38, s[42:43]
	v_pk_mul_f32 v[36:37], v[54:55], v[218:219]
	v_pk_mul_f32 v[40:41], v[50:51], v[214:215]
	v_pk_mul_f32 v[38:39], v[52:53], v[212:213]
	v_pk_mul_f32 v[34:35], v[56:57], v[216:217]
	v_pk_mul_f32 v[40:41], v[58:59], v[40:41] op_sel_hi:[0,1]
	v_pk_mul_f32 v[38:39], v[58:59], v[38:39] op_sel_hi:[0,1]
	v_pk_mul_f32 v[50:51], v[58:59], v[36:37] op_sel_hi:[0,1]
	v_pk_mul_f32 v[36:37], v[58:59], v[34:35] op_sel_hi:[0,1]
	v_cvt_pk_bf16_f32 v34, v38, v39
	v_cvt_pk_bf16_f32 v35, v40, v41
	v_cvt_pk_bf16_f32 v36, v36, v37
	v_cvt_pk_bf16_f32 v37, v50, v51
	v_lshl_add_u64 v[50:51], v[144:145], 1, v[60:61]
	global_store_dwordx4 v[50:51], v[34:37], off
	s_nop 1
	v_pk_mul_f32 v[36:37], v[42:43], v[206:207]
	v_pk_mul_f32 v[40:41], v[46:47], v[222:223]
	v_pk_mul_f32 v[38:39], v[48:49], v[220:221]
	v_pk_mul_f32 v[34:35], v[44:45], v[204:205]
	v_pk_mul_f32 v[40:41], v[58:59], v[40:41] op_sel_hi:[0,1]
	v_pk_mul_f32 v[38:39], v[58:59], v[38:39] op_sel_hi:[0,1]
	v_pk_mul_f32 v[42:43], v[58:59], v[36:37] op_sel_hi:[0,1]
	v_pk_mul_f32 v[36:37], v[58:59], v[34:35] op_sel_hi:[0,1]
	v_cvt_pk_bf16_f32 v34, v38, v39
	v_cvt_pk_bf16_f32 v35, v40, v41
	v_cvt_pk_bf16_f32 v36, v36, v37
	v_cvt_pk_bf16_f32 v37, v42, v43
	global_store_dwordx4 v[50:51], v[34:37], off offset:64
	s_nop 1

.LBB0_552:
	s_andn2_b64 vcc, exec, s[0:1]
	s_cbranch_vccnz .LBB0_554
	v_pk_mul_f32 v[34:35], v[32:33], v[42:43] op_sel_hi:[1,0]
	v_pk_mul_f32 v[36:37], v[30:31], v[42:43] op_sel_hi:[1,0]
	v_pk_mul_f32 v[30:31], v[34:35], v[34:35]
	v_pk_mul_f32 v[32:33], v[36:37], v[36:37]
	v_pk_mul_f32 v[40:41], v[26:27], v[42:43] op_sel_hi:[1,0]
	v_pk_mov_b32 v[38:39], v[32:33], v[30:31] op_sel:[1,0]
	v_mov_b32_e32 v33, v31
	v_pk_add_f32 v[30:31], v[38:39], v[32:33]
	v_pk_mul_f32 v[38:39], v[28:29], v[42:43] op_sel_hi:[1,0]
	v_pk_mul_f32 v[28:29], v[40:41], v[40:41]
	v_pk_mul_f32 v[26:27], v[38:39], v[38:39]
	v_pk_mul_f32 v[32:33], v[22:23], v[42:43] op_sel_hi:[1,0]
	v_pk_add_f32 v[44:45], v[30:31], v[30:31] op_sel_hi:[0,1]
	v_pk_mov_b32 v[30:31], v[28:29], v[26:27] op_sel:[1,0]
	v_mov_b32_e32 v29, v27
	v_mul_f32_e32 v22, v32, v32
	v_pk_add_f32 v[26:27], v[30:31], v[28:29]
	v_pk_mul_f32 v[30:31], v[24:25], v[42:43] op_sel_hi:[1,0]
	v_pk_fma_f32 v[22:23], v[32:33], v[32:33], v[22:23] op_sel_hi:[1,1,0]
	v_pk_add_f32 v[46:47], v[26:27], v[26:27] op_sel_hi:[0,1]
	v_mul_f32_e32 v22, v30, v30
	v_pk_fma_f32 v[24:25], v[30:31], v[30:31], v[22:23] op_sel_hi:[1,1,0]
	v_pk_mul_f32 v[26:27], v[20:21], v[42:43] op_sel_hi:[1,0]
	v_pk_mul_f32 v[28:29], v[18:19], v[42:43] op_sel_hi:[1,0]
	v_mul_f32_e32 v44, v26, v26
	v_mul_f32_e32 v22, v28, v28
	v_mul_f32_e32 v24, v29, v29
	v_mul_f32_e32 v46, v27, v27
	v_pk_add_f32 v[18:19], v[22:23], v[24:25]
	v_pk_add_f32 v[20:21], v[44:45], v[46:47]
	s_and_b64 s[0:1], s[42:43], exec
	v_pk_add_f32 v[18:19], v[18:19], v[20:21]
	s_nop 0
	v_add_f32_e32 v18, v18, v19
	ds_bpermute_b32 v19, v185, v18
	s_waitcnt lgkmcnt(0)
	v_add_f32_e32 v18, v18, v19
	ds_bpermute_b32 v19, v184, v18
	s_waitcnt lgkmcnt(0)
	v_add_f32_e32 v18, v18, v19
	v_fmamk_f32 v18, v18, 0x3c800000, v243
	s_nop 1
	s_cselect_b32 s0, s27, s39
	s_cselect_b32 s1, s26, s38
	v_rsq_f32_e32 v20, v18
	s_nop 0
	v_mov_b32_e32 v18, s1
	v_mov_b32_e32 v19, s0
	v_mul_f32_e32 v21, 0x3e38aa3b, v20
	v_readlane_b32 s0, v251, 43
	v_cndmask_b32_e64 v42, v20, v21, s[42:43]
	v_lshlrev_b64 v[20:21], 11, v[156:157]
	v_readlane_b32 s1, v251, 44
	v_lshl_add_u64 v[46:47], v[144:145], 2, v[18:19]
	s_nop 0
	v_lshl_add_u64 v[22:23], s[0:1], 0, v[20:21]
	v_lshl_add_u64 v[20:21], s[4:5], 0, v[20:21]
	s_movk_i32 s0, 0xf800
	v_lshl_add_u64 v[20:21], s[76:77], 1, v[20:21]
	s_mov_b32 s1, -1
	v_lshl_add_u64 v[22:23], s[64:65], 1, v[22:23]
	v_lshl_add_u64 v[20:21], v[20:21], 0, s[0:1]
	v_cndmask_b32_e64 v45, v21, v23, s[42:43]
	v_cndmask_b32_e64 v44, v20, v22, s[42:43]
	v_pk_mul_f32 v[20:21], v[38:39], v[218:219]
	v_pk_mul_f32 v[24:25], v[34:35], v[214:215]
	v_pk_mul_f32 v[22:23], v[36:37], v[212:213]
	v_pk_mul_f32 v[18:19], v[40:41], v[216:217]
	v_pk_mul_f32 v[24:25], v[42:43], v[24:25] op_sel_hi:[0,1]
	v_pk_mul_f32 v[22:23], v[42:43], v[22:23] op_sel_hi:[0,1]
	v_pk_mul_f32 v[34:35], v[42:43], v[20:21] op_sel_hi:[0,1]
	v_pk_mul_f32 v[20:21], v[42:43], v[18:19] op_sel_hi:[0,1]
	v_cvt_pk_bf16_f32 v18, v22, v23
	v_cvt_pk_bf16_f32 v19, v24, v25
	v_cvt_pk_bf16_f32 v20, v20, v21
	v_cvt_pk_bf16_f32 v21, v34, v35
	v_lshl_add_u64 v[34:35], v[144:145], 1, v[44:45]
	global_store_dwordx4 v[34:35], v[18:21], off
	s_nop 1
	v_pk_mul_f32 v[20:21], v[26:27], v[206:207]
	v_pk_mul_f32 v[24:25], v[30:31], v[222:223]
	v_pk_mul_f32 v[22:23], v[32:33], v[220:221]
	v_pk_mul_f32 v[18:19], v[28:29], v[204:205]
	v_pk_mul_f32 v[24:25], v[42:43], v[24:25] op_sel_hi:[0,1]
	v_pk_mul_f32 v[22:23], v[42:43], v[22:23] op_sel_hi:[0,1]
	v_pk_mul_f32 v[26:27], v[42:43], v[20:21] op_sel_hi:[0,1]
	v_pk_mul_f32 v[20:21], v[42:43], v[18:19] op_sel_hi:[0,1]
	v_cvt_pk_bf16_f32 v18, v22, v23
	v_cvt_pk_bf16_f32 v19, v24, v25
	v_cvt_pk_bf16_f32 v20, v20, v21
	v_cvt_pk_bf16_f32 v21, v26, v27
	global_store_dwordx4 v[34:35], v[18:21], off offset:64
	s_nop 1

.LBB0_556:
	s_andn2_b64 vcc, exec, s[0:1]
	s_cbranch_vccnz .LBB0_558
	v_pk_mul_f32 v[18:19], v[16:17], v[26:27] op_sel_hi:[1,0]
	v_pk_mul_f32 v[20:21], v[14:15], v[26:27] op_sel_hi:[1,0]
	v_pk_mul_f32 v[14:15], v[18:19], v[18:19]
	v_pk_mul_f32 v[16:17], v[20:21], v[20:21]
	v_pk_mul_f32 v[24:25], v[10:11], v[26:27] op_sel_hi:[1,0]
	v_pk_mov_b32 v[22:23], v[16:17], v[14:15] op_sel:[1,0]
	v_mov_b32_e32 v17, v15
	v_pk_add_f32 v[14:15], v[22:23], v[16:17]
	v_pk_mul_f32 v[22:23], v[12:13], v[26:27] op_sel_hi:[1,0]
	v_pk_mul_f32 v[12:13], v[24:25], v[24:25]
	v_pk_mul_f32 v[10:11], v[22:23], v[22:23]
	v_pk_mul_f32 v[16:17], v[6:7], v[26:27] op_sel_hi:[1,0]
	v_pk_add_f32 v[28:29], v[14:15], v[14:15] op_sel_hi:[0,1]
	v_pk_mov_b32 v[14:15], v[12:13], v[10:11] op_sel:[1,0]
	v_mov_b32_e32 v13, v11
	v_mul_f32_e32 v6, v16, v16
	v_pk_add_f32 v[10:11], v[14:15], v[12:13]
	v_pk_mul_f32 v[14:15], v[8:9], v[26:27] op_sel_hi:[1,0]
	v_pk_fma_f32 v[6:7], v[16:17], v[16:17], v[6:7] op_sel_hi:[1,1,0]
	v_pk_add_f32 v[30:31], v[10:11], v[10:11] op_sel_hi:[0,1]
	v_mul_f32_e32 v6, v14, v14
	v_pk_fma_f32 v[8:9], v[14:15], v[14:15], v[6:7] op_sel_hi:[1,1,0]
	v_pk_mul_f32 v[10:11], v[4:5], v[26:27] op_sel_hi:[1,0]
	v_pk_mul_f32 v[12:13], v[2:3], v[26:27] op_sel_hi:[1,0]
	v_mul_f32_e32 v28, v10, v10
	v_mul_f32_e32 v6, v12, v12
	v_mul_f32_e32 v8, v13, v13
	v_mul_f32_e32 v30, v11, v11
	v_pk_add_f32 v[2:3], v[6:7], v[8:9]
	v_pk_add_f32 v[4:5], v[28:29], v[30:31]
	s_and_b64 s[0:1], s[42:43], exec
	v_pk_add_f32 v[2:3], v[2:3], v[4:5]
	s_nop 0
	v_add_f32_e32 v2, v2, v3
	ds_bpermute_b32 v3, v185, v2
	s_waitcnt lgkmcnt(0)
	v_add_f32_e32 v2, v2, v3
	ds_bpermute_b32 v3, v184, v2
	s_waitcnt lgkmcnt(0)
	v_add_f32_e32 v2, v2, v3
	v_fmamk_f32 v2, v2, 0x3c800000, v243
	s_nop 1
	s_cselect_b32 s0, s27, s39
	s_cselect_b32 s1, s26, s38
	v_rsq_f32_e32 v4, v2
	s_nop 0
	v_mov_b32_e32 v2, s1
	v_mov_b32_e32 v3, s0
	v_mul_f32_e32 v5, 0x3e38aa3b, v4
	v_readlane_b32 s0, v251, 43
	v_cndmask_b32_e64 v26, v4, v5, s[42:43]
	v_lshlrev_b64 v[4:5], 11, v[142:143]
	v_readlane_b32 s1, v251, 44
	v_lshl_add_u64 v[30:31], v[144:145], 2, v[2:3]
	s_nop 0
	v_lshl_add_u64 v[6:7], s[0:1], 0, v[4:5]
	v_lshl_add_u64 v[4:5], s[4:5], 0, v[4:5]
	s_movk_i32 s0, 0xf800
	v_lshl_add_u64 v[4:5], s[76:77], 1, v[4:5]
	s_mov_b32 s1, -1
	v_lshl_add_u64 v[6:7], s[64:65], 1, v[6:7]
	v_lshl_add_u64 v[4:5], v[4:5], 0, s[0:1]
	v_cndmask_b32_e64 v29, v5, v7, s[42:43]
	v_cndmask_b32_e64 v28, v4, v6, s[42:43]
	v_pk_mul_f32 v[4:5], v[22:23], v[218:219]
	v_pk_mul_f32 v[8:9], v[18:19], v[214:215]
	v_pk_mul_f32 v[6:7], v[20:21], v[212:213]
	v_pk_mul_f32 v[2:3], v[24:25], v[216:217]
	v_pk_mul_f32 v[8:9], v[26:27], v[8:9] op_sel_hi:[0,1]
	v_pk_mul_f32 v[6:7], v[26:27], v[6:7] op_sel_hi:[0,1]
	v_pk_mul_f32 v[18:19], v[26:27], v[4:5] op_sel_hi:[0,1]
	v_pk_mul_f32 v[4:5], v[26:27], v[2:3] op_sel_hi:[0,1]
	v_cvt_pk_bf16_f32 v2, v6, v7
	v_cvt_pk_bf16_f32 v3, v8, v9
	v_cvt_pk_bf16_f32 v4, v4, v5
	v_cvt_pk_bf16_f32 v5, v18, v19
	v_lshl_add_u64 v[18:19], v[144:145], 1, v[28:29]
	global_store_dwordx4 v[18:19], v[2:5], off
	s_nop 1
	v_pk_mul_f32 v[4:5], v[10:11], v[206:207]
	v_pk_mul_f32 v[8:9], v[14:15], v[222:223]
	v_pk_mul_f32 v[6:7], v[16:17], v[220:221]
	v_pk_mul_f32 v[2:3], v[12:13], v[204:205]
	v_pk_mul_f32 v[8:9], v[26:27], v[8:9] op_sel_hi:[0,1]
	v_pk_mul_f32 v[6:7], v[26:27], v[6:7] op_sel_hi:[0,1]
	v_pk_mul_f32 v[10:11], v[26:27], v[4:5] op_sel_hi:[0,1]
	v_pk_mul_f32 v[4:5], v[26:27], v[2:3] op_sel_hi:[0,1]
	v_cvt_pk_bf16_f32 v2, v6, v7
	v_cvt_pk_bf16_f32 v3, v8, v9
	v_cvt_pk_bf16_f32 v4, v4, v5
	v_cvt_pk_bf16_f32 v5, v10, v11
	global_store_dwordx4 v[18:19], v[2:5], off offset:64
	s_nop 1
